# retention scan output section: packed state fragments put into natural k order with permlane32/16 swaps so each Q fragment is one conflict-free ds_read_b128 (was 2-way conflicted ds_read2_b64), fragme
# speedup vs baseline: 1.0961x; 1.0072x over previous
; #define RET_STORE_K(src) do { \
;         _Pragma("unroll") for (int i = 0; i < 4; ++i) { const int id = tid + 512 * i, s_ = id >> 5, dc = id & 31; *(LAS u32x4*)(L + OFF_K + s_ * QP + dc * 16) = src[i]; } } while (0)
; __device__ __forceinline__ void phase_ret_scan(KP P, const Ctx& c) {
;     ...
;                 *(u32x2*)(O + (size_t)seq_row(b, dir, ck * 64 + i_) * 4096 + h * 512 + dvs * 128 + 16 * w + 4 * q4) = (u32x2){cvt_pk_bf16(a[0], a[1]), cvt_pk_bf16(a[2], a[3])}; }
;             if (has_next) RET_STORE_K(pkn);
; #pragma unroll
;             for (int dt = 0; dt < 16; ++dt) { if ((dt & 1) == 0) asm volatile("" ::: "memory");
;                 f32x4 u = Racc[dt] * gamma;
; #pragma unroll
;                 for (int ks = 0; ks < 2; ++ks) u = __builtin_amdgcn_mfma_f32_16x16x32_bf16(frag16(L + OFF_KT + (16 * dt + r16) * TP + (32 * ks + 8 * q4) * 2), frag16(vtp + 64 * ks), u, 0, 0, 0);
;                 Racc[dt] = u * g63; }
.LBB0_2553:
	v_ashrrev_i32_e32 v47, 31, v46
	s_nop 3
	v_cvt_pk_bf16_f32 v42, v42, v43
	v_cvt_pk_bf16_f32 v43, v44, v45
	v_lshlrev_b64 v[44:45], 13, v[46:47]
	v_lshl_add_u64 v[44:45], v[156:157], 0, v[44:45]
	global_store_dwordx2 v[44:45], v[42:43], off
	s_waitcnt vmcnt(7)
	ds_write_b128 v149, v[26:29] offset:33792
	s_waitcnt vmcnt(6)
	ds_write_b128 v151, v[30:33] offset:33792
	s_waitcnt vmcnt(5)
	ds_write_b128 v197, v[34:37] offset:33792
	s_waitcnt vmcnt(4)
	ds_write_b128 v198, v[38:41] offset:33792
	v_add3_u32 v26, s76, v200, v201
	ds_read_b128 v[48:51], v26 offset:0
	ds_read_b128 v[52:55], v26 offset:64
	ds_read_b128 v[56:59], v26 offset:2304
	ds_read_b128 v[60:63], v26 offset:2368
	ds_read_b128 v[64:67], v26 offset:4608
	ds_read_b128 v[68:71], v26 offset:4672
	ds_read_b128 v[204:207], v26 offset:6912
	ds_read_b128 v[208:211], v26 offset:6976
	ds_read_b128 v[222:225], v26 offset:9216
	ds_read_b128 v[226:229], v26 offset:9280
	v_mov_b32_e32 v149, v148
	v_mov_b32_e32 v151, v150
	v_pk_mul_f32 v[30:31], v[148:149], v[146:147]
	v_pk_mul_f32 v[28:29], v[152:153], v[144:145]
	s_waitcnt lgkmcnt(8)
	s_nop 0
	v_mfma_f32_16x16x32_bf16 v[28:31], v[48:51], v[214:217], v[28:31]
	v_mfma_f32_16x16x32_bf16 v[28:31], v[52:55], v[218:221], v[28:31]
	ds_read_b128 v[230:233], v26 offset:11520
	ds_read_b128 v[234:237], v26 offset:11584
	v_pk_mul_f32 v[34:35], v[148:149], v[106:107]
	v_pk_mul_f32 v[32:33], v[152:153], v[104:105]
	s_waitcnt lgkmcnt(8)
	s_nop 0
	v_mfma_f32_16x16x32_bf16 v[32:35], v[56:59], v[214:217], v[32:35]
	v_mfma_f32_16x16x32_bf16 v[32:35], v[60:63], v[218:221], v[32:35]
	ds_read_b128 v[48:51], v26 offset:13824
	ds_read_b128 v[52:55], v26 offset:13888
	v_pk_mul_f32 v[146:147], v[150:151], v[30:31]
	v_pk_mul_f32 v[144:145], v[154:155], v[28:29]
	v_pk_mul_f32 v[30:31], v[148:149], v[126:127]
	v_pk_mul_f32 v[28:29], v[152:153], v[124:125]
	s_waitcnt lgkmcnt(8)
	s_nop 0
	v_mfma_f32_16x16x32_bf16 v[28:31], v[64:67], v[214:217], v[28:31]
	v_mfma_f32_16x16x32_bf16 v[28:31], v[68:71], v[218:221], v[28:31]
	ds_read_b128 v[56:59], v26 offset:16128
	ds_read_b128 v[60:63], v26 offset:16192
	v_pk_mul_f32 v[106:107], v[150:151], v[34:35]
	v_pk_mul_f32 v[104:105], v[154:155], v[32:33]
	v_pk_mul_f32 v[34:35], v[148:149], v[90:91]
	v_pk_mul_f32 v[32:33], v[152:153], v[88:89]
	s_waitcnt lgkmcnt(8)
	s_nop 0
	v_mfma_f32_16x16x32_bf16 v[32:35], v[204:207], v[214:217], v[32:35]
	v_mfma_f32_16x16x32_bf16 v[32:35], v[208:211], v[218:221], v[32:35]
	ds_read_b128 v[64:67], v26 offset:18432
	ds_read_b128 v[68:71], v26 offset:18496
	v_pk_mul_f32 v[126:127], v[150:151], v[30:31]
	v_pk_mul_f32 v[124:125], v[154:155], v[28:29]
	v_pk_mul_f32 v[30:31], v[148:149], v[118:119]
	v_pk_mul_f32 v[28:29], v[152:153], v[116:117]
	s_waitcnt lgkmcnt(8)
	s_nop 0
	v_mfma_f32_16x16x32_bf16 v[28:31], v[222:225], v[214:217], v[28:31]
	v_mfma_f32_16x16x32_bf16 v[28:31], v[226:229], v[218:221], v[28:31]
	ds_read_b128 v[204:207], v26 offset:20736
	ds_read_b128 v[208:211], v26 offset:20800
	v_pk_mul_f32 v[90:91], v[150:151], v[34:35]
	v_pk_mul_f32 v[88:89], v[154:155], v[32:33]
	v_pk_mul_f32 v[34:35], v[148:149], v[142:143]
	v_pk_mul_f32 v[32:33], v[152:153], v[140:141]
	s_waitcnt lgkmcnt(8)
	s_nop 0
	v_mfma_f32_16x16x32_bf16 v[32:35], v[230:233], v[214:217], v[32:35]
	v_mfma_f32_16x16x32_bf16 v[32:35], v[234:237], v[218:221], v[32:35]
	ds_read_b128 v[222:225], v26 offset:23040
	ds_read_b128 v[226:229], v26 offset:23104
	v_pk_mul_f32 v[118:119], v[150:151], v[30:31]
	v_pk_mul_f32 v[116:117], v[154:155], v[28:29]
	v_pk_mul_f32 v[30:31], v[148:149], v[110:111]
	v_pk_mul_f32 v[28:29], v[152:153], v[108:109]
	s_waitcnt lgkmcnt(8)
	s_nop 0
	v_mfma_f32_16x16x32_bf16 v[28:31], v[48:51], v[214:217], v[28:31]
	v_mfma_f32_16x16x32_bf16 v[28:31], v[52:55], v[218:221], v[28:31]
	ds_read_b128 v[230:233], v26 offset:25344
	ds_read_b128 v[234:237], v26 offset:25408
	v_pk_mul_f32 v[142:143], v[150:151], v[34:35]
	v_pk_mul_f32 v[140:141], v[154:155], v[32:33]
	v_pk_mul_f32 v[34:35], v[148:149], v[134:135]
	v_pk_mul_f32 v[32:33], v[152:153], v[132:133]
	s_waitcnt lgkmcnt(8)
	s_nop 0
	v_mfma_f32_16x16x32_bf16 v[32:35], v[56:59], v[214:217], v[32:35]
	v_mfma_f32_16x16x32_bf16 v[32:35], v[60:63], v[218:221], v[32:35]
	ds_read_b128 v[48:51], v26 offset:27648
	ds_read_b128 v[52:55], v26 offset:27712
	v_pk_mul_f32 v[110:111], v[150:151], v[30:31]
	v_pk_mul_f32 v[108:109], v[154:155], v[28:29]
	v_pk_mul_f32 v[30:31], v[148:149], v[102:103]
	v_pk_mul_f32 v[28:29], v[152:153], v[100:101]
	s_waitcnt lgkmcnt(8)
	s_nop 0
	v_mfma_f32_16x16x32_bf16 v[28:31], v[64:67], v[214:217], v[28:31]
	v_mfma_f32_16x16x32_bf16 v[28:31], v[68:71], v[218:221], v[28:31]
	ds_read_b128 v[56:59], v26 offset:29952
	ds_read_b128 v[60:63], v26 offset:30016
	v_pk_mul_f32 v[134:135], v[150:151], v[34:35]
	v_pk_mul_f32 v[132:133], v[154:155], v[32:33]
	v_pk_mul_f32 v[34:35], v[148:149], v[130:131]
	v_pk_mul_f32 v[32:33], v[152:153], v[128:129]
	s_waitcnt lgkmcnt(8)
	s_nop 0
	v_mfma_f32_16x16x32_bf16 v[32:35], v[204:207], v[214:217], v[32:35]
	v_mfma_f32_16x16x32_bf16 v[32:35], v[208:211], v[218:221], v[32:35]
	ds_read_b128 v[64:67], v26 offset:32256
	ds_read_b128 v[68:71], v26 offset:32320
	v_pk_mul_f32 v[102:103], v[150:151], v[30:31]
	v_pk_mul_f32 v[100:101], v[154:155], v[28:29]
	v_pk_mul_f32 v[30:31], v[148:149], v[98:99]
	v_pk_mul_f32 v[28:29], v[152:153], v[96:97]
	s_waitcnt lgkmcnt(8)
	s_nop 0
	v_mfma_f32_16x16x32_bf16 v[28:31], v[222:225], v[214:217], v[28:31]
	v_mfma_f32_16x16x32_bf16 v[28:31], v[226:229], v[218:221], v[28:31]
	ds_read_b128 v[204:207], v26 offset:34560
	ds_read_b128 v[208:211], v26 offset:34624
	v_pk_mul_f32 v[130:131], v[150:151], v[34:35]
	v_pk_mul_f32 v[128:129], v[154:155], v[32:33]
	v_pk_mul_f32 v[34:35], v[148:149], v[122:123]
	v_pk_mul_f32 v[32:33], v[152:153], v[120:121]
	s_waitcnt lgkmcnt(8)
; #define LAS __attribute__((address_space(3)))
; __device__ __forceinline__ void phase_ret_scan(KP P, const Ctx& c) {
;     ...
;             asm volatile("" : "+v"(tid));
;             const int lane = tid & 63, r16 = lane & 15, q4 = lane >> 4;
;             __syncthreads();
; #pragma unroll
;             for (int i = 0; i < 4; ++i) { const int id = tid + 512 * i, s_ = id >> 5, dc = id & 31; *(LAS u32x4*)(L + OFF_Q + s_ * QP + dc * 16) = pq[i]; }
; #pragma unroll
;             for (int i = 0; i < 2; ++i) { const int id = tid + 512 * i, s_ = id >> 4, ec = id & 15; *(LAS u32x4*)(L + OFF_P + s_ * VP + ec * 16) = pv[i]; }
;             __syncthreads();
;             if (ck + 1 < SLEN / 64) RET_LOAD_QV(ck + 1);
;     ...
;             for (int dt = 0; dt < 16; ++dt) { if ((dt & 1) == 0) asm volatile("" ::: "memory");
;                 f32x4 u = Racc[dt] * gamma;
; #pragma unroll
;                 for (int ks = 0; ks < 2; ++ks) u = __builtin_amdgcn_mfma_f32_16x16x32_bf16(frag16(L + OFF_KT + (16 * dt + r16) * TP + (32 * ks + 8 * q4) * 2), frag16(vtp + 64 * ks), u, 0, 0, 0);
;                 Racc[dt] = u * g63; }
	s_nop 0
	v_mfma_f32_16x16x32_bf16 v[32:35], v[230:233], v[214:217], v[32:35]
	v_mfma_f32_16x16x32_bf16 v[32:35], v[234:237], v[218:221], v[32:35]
	v_pk_mul_f32 v[98:99], v[150:151], v[30:31]
	v_pk_mul_f32 v[96:97], v[154:155], v[28:29]
	v_pk_mul_f32 v[30:31], v[148:149], v[94:95]
	v_pk_mul_f32 v[28:29], v[152:153], v[92:93]
	s_waitcnt lgkmcnt(6)
	s_nop 0
	v_mfma_f32_16x16x32_bf16 v[28:31], v[48:51], v[214:217], v[28:31]
	v_mfma_f32_16x16x32_bf16 v[28:31], v[52:55], v[218:221], v[28:31]
	v_pk_mul_f32 v[122:123], v[150:151], v[34:35]
	v_pk_mul_f32 v[120:121], v[154:155], v[32:33]
	v_pk_mul_f32 v[34:35], v[148:149], v[114:115]
	v_pk_mul_f32 v[32:33], v[152:153], v[112:113]
	s_waitcnt lgkmcnt(4)
	s_nop 0
	v_mfma_f32_16x16x32_bf16 v[32:35], v[56:59], v[214:217], v[32:35]
	v_mfma_f32_16x16x32_bf16 v[32:35], v[60:63], v[218:221], v[32:35]
	v_pk_mul_f32 v[94:95], v[150:151], v[30:31]
	v_pk_mul_f32 v[92:93], v[154:155], v[28:29]
	v_pk_mul_f32 v[30:31], v[148:149], v[86:87]
	v_pk_mul_f32 v[28:29], v[152:153], v[84:85]
	s_waitcnt lgkmcnt(2)
	s_nop 0
	v_mfma_f32_16x16x32_bf16 v[28:31], v[64:67], v[214:217], v[28:31]
	v_mfma_f32_16x16x32_bf16 v[28:31], v[68:71], v[218:221], v[28:31]
	v_pk_mul_f32 v[114:115], v[150:151], v[34:35]
	v_pk_mul_f32 v[112:113], v[154:155], v[32:33]
	v_pk_mul_f32 v[34:35], v[148:149], v[138:139]
	v_pk_mul_f32 v[32:33], v[152:153], v[136:137]
	s_waitcnt lgkmcnt(0)
	s_nop 0
	v_mfma_f32_16x16x32_bf16 v[32:35], v[204:207], v[214:217], v[32:35]
	v_mfma_f32_16x16x32_bf16 v[32:35], v[208:211], v[218:221], v[32:35]
	v_pk_mul_f32 v[86:87], v[150:151], v[30:31]
	v_pk_mul_f32 v[84:85], v[154:155], v[28:29]
	s_nop 5
	v_pk_mul_f32 v[138:139], v[150:151], v[34:35]
	v_pk_mul_f32 v[136:137], v[154:155], v[32:33]
	s_add_i32 s25, s25, 64
	s_sub_i32 s24, s24, 64
	s_add_i32 s26, s26, 1
	s_cmpk_eq_i32 s25, 0x10c0
	s_cbranch_scc1 .LBB0_2551
.LBB0_2554:
	s_waitcnt lgkmcnt(0)
	v_lshlrev_b32_e32 v26, 4, v195
	v_and_b32_e32 v78, 0x1f0, v26
	v_ashrrev_i32_e32 v29, 5, v195
	v_add_u32_e32 v27, 0, v78
	v_mul_lo_u32 v28, v29, s15
	v_add_u32_e32 v149, v27, v28
	s_barrier
	s_waitcnt vmcnt(5)
	ds_write_b128 v149, v[2:5]
	v_add_u32_e32 v3, 0x200, v195
	v_ashrrev_i32_e32 v30, 5, v3
	v_mul_lo_u32 v2, v30, s15
	v_add_u32_e32 v151, v27, v2
	v_add_u32_e32 v2, 0x400, v195
	v_ashrrev_i32_e32 v32, 5, v2
	v_mul_lo_u32 v2, v32, s15
	v_add_u32_e32 v197, v27, v2
	v_add_u32_e32 v2, 0x600, v195
	v_ashrrev_i32_e32 v33, 5, v2
	v_mul_lo_u32 v2, v33, s15
	v_and_b32_e32 v28, 0xf0, v26
	v_add_u32_e32 v198, v27, v2
	v_add_u32_e32 v2, s17, v28
	v_ashrrev_i32_e32 v37, 4, v195
	v_ashrrev_i32_e32 v40, 4, v3
	v_mad_u64_u32 v[4:5], s[0:1], v37, s18, v[2:3]
	v_mad_u64_u32 v[2:3], s[0:1], v40, s18, v[2:3]
	s_waitcnt vmcnt(4)
	ds_write_b128 v151, v[6:9]
	s_waitcnt vmcnt(3)
	ds_write_b128 v197, v[10:13]
	s_waitcnt vmcnt(2)
	ds_write_b128 v198, v[14:17]
	s_waitcnt vmcnt(1)
	ds_write_b128 v4, v[18:21]
	s_waitcnt vmcnt(0)
	ds_write_b128 v2, v[22:25]
	v_add_u32_e32 v2, s25, v29
	v_add_u32_e32 v3, 64, v2
	v_add_u32_e32 v6, s25, v30
	v_cmp_gt_i32_e32 vcc, s96, v3
	v_add_u32_e32 v2, 0xffffff40, v2
	v_mov_b32_e32 v24, s22
	v_mov_b32_e32 v25, s23
	v_add_u32_e32 v7, 64, v6
	v_add_u32_e32 v10, s25, v32
	v_cndmask_b32_e32 v4, v191, v192, vcc
	v_cndmask_b32_e32 v2, v2, v3, vcc
	v_cndmask_b32_e32 v3, v24, v25, vcc
	v_cmp_gt_i32_e32 vcc, s96, v7
	v_add_u32_e32 v6, 0xffffff40, v6
	v_add_u32_e32 v11, 64, v10
	v_add_u32_e32 v16, s25, v33
	v_cndmask_b32_e32 v8, v191, v192, vcc
	v_cndmask_b32_e32 v6, v6, v7, vcc
	v_cndmask_b32_e32 v7, v24, v25, vcc
	v_cmp_gt_i32_e32 vcc, s96, v11
	v_add_u32_e32 v10, 0xffffff40, v10
	v_add_u32_e32 v17, 64, v16
	v_cndmask_b32_e32 v12, v191, v192, vcc
	v_cndmask_b32_e32 v10, v10, v11, vcc
	v_cndmask_b32_e32 v11, v24, v25, vcc
	v_cmp_gt_i32_e32 vcc, s96, v17
	v_add_u32_e32 v16, 0xffffff40, v16
	v_sub_u32_e32 v4, v4, v29
	v_cndmask_b32_e32 v18, v191, v192, vcc
	v_sub_u32_e32 v18, v18, v33
	v_add_u32_e32 v18, s24, v18
	v_cndmask_b32_e32 v16, v16, v17, vcc
	v_add_u32_e32 v18, 0xffffeec1, v18
	v_cndmask_b32_e64 v16, v18, v16, s[54:55]
	v_mov_b32_e32 v29, v79
	v_add_u32_e32 v18, s25, v37
	v_lshl_add_u64 v[22:23], s[66:67], 0, v[28:29]
	v_add_u32_e32 v19, 64, v18
	v_add_u32_e32 v28, s25, v40
	v_cndmask_b32_e32 v17, v24, v25, vcc
	v_cmp_gt_i32_e32 vcc, s96, v19
	v_add_u32_e32 v18, 0xffffff40, v18
	v_add_u32_e32 v29, 64, v28
	v_cndmask_b32_e32 v20, v191, v192, vcc
	v_cndmask_b32_e32 v18, v18, v19, vcc
	v_cndmask_b32_e32 v19, v24, v25, vcc
	v_cmp_gt_i32_e32 vcc, s96, v29
	v_sub_u32_e32 v12, v12, v32
	v_and_b32_e32 v36, 63, v195
	v_cndmask_b32_e32 v32, v191, v192, vcc
	v_sub_u32_e32 v8, v8, v30
	v_sub_u32_e32 v20, v20, v37
	v_cndmask_b32_e32 v24, v24, v25, vcc
	v_sub_u32_e32 v25, v32, v40
	v_add_u32_e32 v4, s24, v4
	v_add_u32_e32 v8, s24, v8
	v_add_u32_e32 v12, s24, v12
	v_add_u32_e32 v20, s24, v20
	v_add_u32_e32 v28, 0xffffff40, v28
	v_add_u32_e32 v25, s24, v25
	v_mad_u32_u24 v32, v36, s15, 0
	v_add_u32_e32 v4, 0xffffeec1, v4
	v_add_u32_e32 v8, 0xffffeec1, v8
	v_add_u32_e32 v12, 0xffffeec1, v12
	v_add_u32_e32 v20, 0xffffeec1, v20
	v_cndmask_b32_e32 v28, v28, v29, vcc
	v_add_u32_e32 v25, 0xffffeec1, v25
	v_add_u32_e32 v37, s60, v32
	s_waitcnt lgkmcnt(0)
	s_barrier
; #define LAS __attribute__((address_space(3)))
; __device__ __forceinline__ void unpack8(const u32x4 u, float (&f)[8]) { f[0] = bflo(u.x); f[1] = bfhi(u.x); f[2] = bflo(u.y); f[3] = bfhi(u.y); f[4] = bflo(u.z); f[5] = bfhi(u.z); f[6] = bflo(u.w); f[7] = bfhi(u.w); }
; __device__ __forceinline__ void phase_ret_scan(KP P, const Ctx& c) {
;     ...
;             if (ck + 1 < SLEN / 64) RET_LOAD_QV(ck + 1);
;             {   const float vs = exp2f(-lg2 * (float)lane);
; #pragma unroll
;                 for (int i = 0; i < 4; ++i) { const int dc = w + 8 * i;
;                     const u32x4 raw = *(const LAS u32x4*)(L + OFF_K + lane * QP + dc * 16);
; #pragma unroll
;                     for (int e = 0; e < 4; ++e) { *(LAS unsigned short*)(L + OFF_KT + (dc * 8 + 2 * e) * TP + lane * 2) = (unsigned short)(raw[e] & 0xffffu); *(LAS unsigned short*)(L + OFF_KT + (dc * 8 + 2 * e + 1) * TP + lane * 2) = (unsigned short)(raw[e] >> 16); } }
; #pragma unroll
;                 for (int i = 0; i < 2; ++i) { const int ec = w + 8 * i; float t8[8]; unpack8(*(const LAS u32x4*)(L + OFF_P + lane * VP + ec * 16), t8);
; #pragma unroll
;                     for (int e = 0; e < 4; ++e) { const unsigned pk2 = cvt_pk_bf16(t8[2 * e] * vs, t8[2 * e + 1] * vs);
;                         *(LAS unsigned short*)(L + OFF_VT + (ec * 8 + 2 * e) * TP + lane * 2) = (unsigned short)(pk2 & 0xffffu); *(LAS unsigned short*)(L + OFF_VT + (ec * 8 + 2 * e + 1) * TP + lane * 2) = (unsigned short)(pk2 >> 16); } } }
	v_cndmask_b32_e64 v2, v4, v2, s[54:55]
	v_cndmask_b32_e64 v6, v8, v6, s[54:55]
	v_cndmask_b32_e64 v10, v12, v10, s[54:55]
	v_cndmask_b32_e64 v18, v20, v18, s[54:55]
	v_cndmask_b32_e64 v25, v25, v28, s[54:55]
	ds_read_b128 v[44:47], v37 offset:33792
	v_add_u32_e32 v2, v2, v3
	v_add_u32_e32 v6, v6, v7
	v_add_u32_e32 v10, v10, v11
	v_add_u32_e32 v16, v16, v17
	v_add_u32_e32 v18, v18, v19
	v_add_u32_e32 v24, v25, v24
	v_ashrrev_i32_e32 v3, 31, v2
	v_ashrrev_i32_e32 v7, 31, v6
	v_ashrrev_i32_e32 v11, 31, v10
	v_ashrrev_i32_e32 v17, 31, v16
	v_ashrrev_i32_e32 v19, 31, v18
	v_ashrrev_i32_e32 v25, 31, v24
	v_lshl_add_u64 v[14:15], s[64:65], 0, v[78:79]
	v_lshlrev_b64 v[26:27], 12, v[2:3]
	v_lshlrev_b64 v[30:31], 12, v[6:7]
	v_lshlrev_b64 v[34:35], 12, v[10:11]
	v_lshlrev_b64 v[38:39], 12, v[16:17]
	v_lshlrev_b64 v[18:19], 13, v[18:19]
	v_lshlrev_b64 v[24:25], 13, v[24:25]
	v_lshlrev_b32_e32 v33, 1, v36
	v_lshl_add_u64 v[2:3], v[14:15], 0, v[26:27]
	v_lshl_add_u64 v[6:7], v[14:15], 0, v[30:31]
	v_lshl_add_u64 v[10:11], v[14:15], 0, v[34:35]
	v_lshl_add_u64 v[14:15], v[14:15], 0, v[38:39]
	v_lshl_add_u64 v[18:19], v[22:23], 0, v[18:19]
	v_lshl_add_u64 v[22:23], v[22:23], 0, v[24:25]
	v_add_u32_e32 v40, s77, v33
	v_add_u32_e32 v37, s76, v33
	global_load_dwordx4 v[2:5], v[2:3], off
	v_add_u32_e32 v41, s3, v33
	global_load_dwordx4 v[6:9], v[6:7], off
	v_cvt_f32_ubyte0_e32 v28, v36
	global_load_dwordx4 v[10:13], v[10:11], off
	v_mul_f32_e64 v29, -v194, v28
	global_load_dwordx4 v[14:17], v[14:15], off
	v_cmp_gt_f32_e32 vcc, s16, v29
	global_load_dwordx4 v[18:21], v[18:19], off
	v_and_b32_e32 v199, 15, v195
	global_load_dwordx4 v[22:25], v[22:23], off
	s_waitcnt lgkmcnt(0)
	ds_write_b16 v40, v44
	ds_write_b16_d16_hi v40, v44 offset:144
	v_add_u32_e32 v40, s78, v37
	ds_write_b16 v40, v45
	v_add_u32_e32 v40, s79, v33
	ds_write_b16_d16_hi v40, v45 offset:144
	v_add_u32_e32 v40, s80, v37
	ds_write_b16 v40, v46
	v_add_u32_e32 v40, s81, v33
	ds_write_b16_d16_hi v40, v46 offset:144
	v_add_u32_e32 v40, s82, v37
	ds_write_b16 v40, v47
	v_add_u32_e32 v40, s83, v33
	ds_write_b16_d16_hi v40, v47 offset:144
	v_add_u32_e32 v40, s84, v32
	ds_read_b128 v[44:47], v40 offset:33792
	v_add_u32_e32 v40, s86, v37
	s_waitcnt lgkmcnt(0)
	ds_write_b16 v41, v44
	ds_write_b16_d16_hi v41, v44 offset:144
	ds_write_b16 v40, v45
	v_add_u32_e32 v40, s87, v33
	ds_write_b16_d16_hi v40, v45 offset:144
	v_add_u32_e32 v40, s88, v37
	v_add_u32_e32 v37, s90, v37
	ds_write_b16 v40, v46
	v_add_u32_e32 v40, s89, v33
	ds_write_b16 v37, v47
	v_add_u32_e32 v37, s91, v33
	ds_write_b16_d16_hi v40, v46 offset:144
	ds_write_b16_d16_hi v37, v47 offset:144
	v_add_u32_e32 v37, s97, v32
	ds_read_b128 v[44:47], v37 offset:33792
	v_cndmask_b32_e32 v29, 0, v185, vcc
	v_add_u32_e32 v40, s94, v33
	v_fma_f32 v28, -v194, v28, v29
	s_waitcnt lgkmcnt(0)
	ds_write_b16 v40, v44
	ds_write_b16_d16_hi v40, v44 offset:144
	ds_write_b16 v40, v45 offset:288
	ds_write_b16_d16_hi v40, v45 offset:432
	ds_write_b16 v40, v46 offset:576
	ds_write_b16_d16_hi v40, v46 offset:720
	ds_write_b16 v40, v47 offset:864
	ds_write_b16_d16_hi v40, v47 offset:1008
	v_add_u32_e32 v32, s95, v32
	v_exp_f32_e32 v28, v28
	ds_read_b128 v[44:47], v32 offset:33792
	v_cndmask_b32_e32 v29, 0, v193, vcc
	v_add_u32_e32 v37, s85, v33
	v_ldexp_f32 v28, v28, v29
	v_mov_b32_e32 v29, s17
	v_mad_u32_u24 v29, v36, s18, v29
	s_waitcnt lgkmcnt(0)
	ds_write_b16 v37, v44
	ds_write_b16_d16_hi v37, v44 offset:144
	ds_write_b16 v37, v45 offset:288
	ds_write_b16_d16_hi v37, v45 offset:432
	ds_write_b16 v37, v46 offset:576
	ds_write_b16_d16_hi v37, v46 offset:720
	ds_write_b16 v37, v47 offset:864
	ds_write_b16_d16_hi v37, v47 offset:1008
	v_add_u32_e32 v32, s60, v29
	ds_read_b128 v[44:47], v32
	v_add_u32_e32 v29, s84, v29
	v_and_b32_e32 v200, 48, v195
	v_bfe_u32 v42, v195, 4, 2
	v_lshlrev_b32_e32 v156, 2, v42
	s_waitcnt lgkmcnt(0)
	v_lshlrev_b32_e32 v32, 16, v44
	v_and_b32_e32 v36, 0xffff0000, v44
	v_mul_f32_e32 v32, v28, v32
	v_lshlrev_b32_e32 v37, 16, v45
	v_lshlrev_b32_e32 v41, 16, v46
	v_and_b32_e32 v43, 0xffff0000, v46
	v_mul_f32_e32 v36, v28, v36
	v_cvt_pk_bf16_f32 v32, v32, s0
	v_add_u32_e32 v46, s5, v33
	v_and_b32_e32 v40, 0xffff0000, v45
	v_cvt_pk_bf16_f32 v36, v36, s0
	ds_write_b16 v46, v32
	ds_write_b16 v46, v36 offset:144
	v_mul_f32_e32 v32, v28, v37
	v_add_u32_e32 v37, s4, v33
	v_mul_f32_e32 v36, v28, v40
	v_cvt_pk_bf16_f32 v32, v32, s0
	v_add_u32_e32 v40, s78, v37
	v_cvt_pk_bf16_f32 v36, v36, s0
	ds_write_b16 v40, v32
	v_add_u32_e32 v32, s8, v33
	ds_write_b16 v32, v36 offset:144
	v_mul_f32_e32 v32, v28, v41
	v_mul_f32_e32 v36, v28, v43
	v_cvt_pk_bf16_f32 v32, v32, s0
	v_add_u32_e32 v40, s80, v37
	v_lshlrev_b32_e32 v44, 16, v47
	v_cvt_pk_bf16_f32 v36, v36, s0
	ds_write_b16 v40, v32
	v_add_u32_e32 v32, s9, v33
	v_and_b32_e32 v45, 0xffff0000, v47
	ds_write_b16 v32, v36 offset:144
	v_mul_f32_e32 v32, v28, v44
	v_mul_f32_e32 v36, v28, v45
	v_cvt_pk_bf16_f32 v32, v32, s0
	v_add_u32_e32 v40, s82, v37
	v_cvt_pk_bf16_f32 v36, v36, s0
	ds_write_b16 v40, v32
	v_add_u32_e32 v32, s10, v33
	ds_write_b16 v32, v36 offset:144
	ds_read_b128 v[44:47], v29
	v_lshl_add_u32 v205, v42, 3, 0
	v_cvt_pk_bf16_f32 v70, v116, v117
	v_cvt_pk_bf16_f32 v71, v118, v119
	v_cvt_pk_bf16_f32 v72, v140, v141
	s_waitcnt lgkmcnt(0)
; #define LAS __attribute__((address_space(3)))
; __device__ __forceinline__ void unpack8(const u32x4 u, float (&f)[8]) { f[0] = bflo(u.x); f[1] = bfhi(u.x); f[2] = bflo(u.y); f[3] = bfhi(u.y); f[4] = bflo(u.z); f[5] = bfhi(u.z); f[6] = bflo(u.w); f[7] = bfhi(u.w); }
; __device__ __forceinline__ void phase_ret_scan(KP P, const Ctx& c) {
;     ...
; #pragma unroll
;                 for (int i = 0; i < 2; ++i) { const int ec = w + 8 * i; float t8[8]; unpack8(*(const LAS u32x4*)(L + OFF_P + lane * VP + ec * 16), t8);
; #pragma unroll
;                     for (int e = 0; e < 4; ++e) { const unsigned pk2 = cvt_pk_bf16(t8[2 * e] * vs, t8[2 * e + 1] * vs);
;                         *(LAS unsigned short*)(L + OFF_VT + (ec * 8 + 2 * e) * TP + lane * 2) = (unsigned short)(pk2 & 0xffffu); *(LAS unsigned short*)(L + OFF_VT + (ec * 8 + 2 * e + 1) * TP + lane * 2) = (unsigned short)(pk2 >> 16); } } }
;             const int it_s = w >> 1, jt0 = 2 * (w & 1);
;             f32x4 s0 = (f32x4){0.f, 0.f, 0.f, 0.f}, s1 = s0;
; #pragma unroll
;             for (int ks = 0; ks < 8; ++ks) { const int co = (32 * ks + 8 * q4) * 2; if ((ks & 1) == 0) asm volatile("" ::: "memory");
;                 const bf16x8 qf = frag16(L + OFF_Q + (16 * it_s + r16) * QP + co), k0 = frag16(L + OFF_K + (16 * jt0 + r16) * QP + co), k1 = frag16(L + OFF_K + (16 * jt0 + 16 + r16) * QP + co);
;                 s0 = __builtin_amdgcn_mfma_f32_16x16x32_bf16(k0, qf, s0, 0, 0, 0); s1 = __builtin_amdgcn_mfma_f32_16x16x32_bf16(k1, qf, s1, 0, 0, 0); }
;             __syncthreads();
;             {   const int i_ = 16 * it_s + r16; const float gi = exp2f(lg2 * (float)i_);
;                 const int j0 = 16 * jt0 + 4 * q4, j1 = j0 + 16; float p0[4], p1[4];
; #pragma unroll
;                 for (int r = 0; r < 4; ++r) { p0[r] = (j0 + r <= i_) ? s0[r] * gi : 0.f; p1[r] = (j1 + r <= i_) ? s1[r] * gi : 0.f; }
;                 *(LAS u32x2*)(L + OFF_P + i_ * TP + j0 * 2) = (u32x2){cvt_pk_bf16(p0[0], p0[1]), cvt_pk_bf16(p0[2], p0[3])};
;                 *(LAS u32x2*)(L + OFF_P + i_ * TP + j1 * 2) = (u32x2){cvt_pk_bf16(p1[0], p1[1]), cvt_pk_bf16(p1[2], p1[3])}; }
;             __syncthreads();
	v_lshlrev_b32_e32 v29, 16, v44
	v_and_b32_e32 v32, 0xffff0000, v44
	v_mul_f32_e32 v29, v28, v29
	v_lshlrev_b32_e32 v36, 16, v45
	v_lshlrev_b32_e32 v41, 16, v46
	v_and_b32_e32 v43, 0xffff0000, v46
	v_mul_f32_e32 v32, v28, v32
	v_cvt_pk_bf16_f32 v29, v29, s0
	v_add_u32_e32 v46, s11, v33
	v_and_b32_e32 v40, 0xffff0000, v45
	v_cvt_pk_bf16_f32 v32, v32, s0
	ds_write_b16 v46, v29
	ds_write_b16 v46, v32 offset:144
	v_mul_f32_e32 v29, v28, v36
	v_mul_f32_e32 v32, v28, v40
	v_cvt_pk_bf16_f32 v29, v29, s0
	v_add_u32_e32 v36, s86, v37
	v_cvt_pk_bf16_f32 v32, v32, s0
	ds_write_b16 v36, v29
	v_add_u32_e32 v29, s12, v33
	ds_write_b16 v29, v32 offset:144
	v_mul_f32_e32 v29, v28, v41
	v_mul_f32_e32 v32, v28, v43
	v_cvt_pk_bf16_f32 v29, v29, s0
	v_add_u32_e32 v36, s88, v37
	v_lshlrev_b32_e32 v44, 16, v47
	v_cvt_pk_bf16_f32 v32, v32, s0
	ds_write_b16 v36, v29
	v_add_u32_e32 v29, s13, v33
	v_and_b32_e32 v45, 0xffff0000, v47
	ds_write_b16 v29, v32 offset:144
	v_mul_f32_e32 v29, v28, v44
	v_mul_f32_e32 v28, v28, v45
	v_cvt_pk_bf16_f32 v29, v29, s0
	v_add_u32_e32 v32, s90, v37
	v_cvt_pk_bf16_f32 v28, v28, s0
	ds_write_b16 v32, v29
	v_add_u32_e32 v29, s14, v33
	ds_write_b16 v29, v28 offset:144
	v_or_b32_e32 v32, s75, v199
	v_or_b32_e32 v29, s74, v199
	v_mul_lo_u32 v28, v32, s15
	v_mul_u32_u24_e32 v29, 0x210, v29
	v_add3_u32 v28, 0, v28, v200
	v_add3_u32 v29, 0, v29, v200
	ds_read_b128 v[44:47], v28
	ds_read_b128 v[48:51], v29 offset:33792
	ds_read_b128 v[52:55], v29 offset:42240
	s_waitcnt lgkmcnt(1)
	v_mfma_f32_16x16x32_bf16 v[48:51], v[48:51], v[44:47], 0
	v_or_b32_e32 v33, s74, v156
	v_cmp_le_i32_e64 s[56:57], v33, v32
	v_or_b32_e32 v36, 16, v33
	s_waitcnt lgkmcnt(0)
	v_mfma_f32_16x16x32_bf16 v[44:47], v[52:55], v[44:47], 0
	ds_read_b128 v[52:55], v29 offset:42304
	ds_read_b128 v[56:59], v29 offset:33856
	ds_read_b128 v[60:63], v28 offset:64
	v_or_b32_e32 v41, 17, v33
	s_waitcnt lgkmcnt(0)
	v_mfma_f32_16x16x32_bf16 v[48:51], v[56:59], v[60:63], v[48:51]
	v_cvt_pk_bf16_f32 v73, v142, v143
	v_add_u32_e32 v204, s17, v200
	s_cmp_gt_u32 s26, 3
	v_mfma_f32_16x16x32_bf16 v[44:47], v[52:55], v[60:63], v[44:47]
	ds_read_b128 v[52:55], v28 offset:128
	ds_read_b128 v[56:59], v29 offset:33920
	ds_read_b128 v[60:63], v29 offset:42368
	s_cselect_b64 s[38:39], -1, 0
	v_add_u32_e32 v202, s25, v199
	s_waitcnt lgkmcnt(1)
	v_mfma_f32_16x16x32_bf16 v[48:51], v[56:59], v[52:55], v[48:51]
	v_sub_u32_e32 v203, s24, v199
	s_waitcnt lgkmcnt(0)
	v_mfma_f32_16x16x32_bf16 v[44:47], v[60:63], v[52:55], v[44:47]
	ds_read_b128 v[52:55], v29 offset:42432
	ds_read_b128 v[56:59], v29 offset:33984
	ds_read_b128 v[60:63], v28 offset:192
	s_waitcnt lgkmcnt(0)
	v_mfma_f32_16x16x32_bf16 v[48:51], v[56:59], v[60:63], v[48:51]
	v_mfma_f32_16x16x32_bf16 v[44:47], v[52:55], v[60:63], v[44:47]
	ds_read_b128 v[52:55], v28 offset:256
	ds_read_b128 v[56:59], v29 offset:34048
	ds_read_b128 v[60:63], v29 offset:42496
	s_waitcnt lgkmcnt(1)
	v_mfma_f32_16x16x32_bf16 v[48:51], v[56:59], v[52:55], v[48:51]
	s_waitcnt lgkmcnt(0)
	v_mfma_f32_16x16x32_bf16 v[44:47], v[60:63], v[52:55], v[44:47]
	ds_read_b128 v[52:55], v29 offset:42560
	ds_read_b128 v[56:59], v29 offset:34112
	ds_read_b128 v[60:63], v28 offset:320
	s_waitcnt lgkmcnt(0)
	v_mfma_f32_16x16x32_bf16 v[48:51], v[56:59], v[60:63], v[48:51]
	v_mfma_f32_16x16x32_bf16 v[44:47], v[52:55], v[60:63], v[44:47]
	ds_read_b128 v[52:55], v28 offset:384
	ds_read_b128 v[56:59], v29 offset:34176
	ds_read_b128 v[60:63], v29 offset:42624
	s_waitcnt lgkmcnt(1)
	v_mfma_f32_16x16x32_bf16 v[48:51], v[56:59], v[52:55], v[48:51]
	s_waitcnt lgkmcnt(0)
	v_mfma_f32_16x16x32_bf16 v[44:47], v[60:63], v[52:55], v[44:47]
	ds_read_b128 v[52:55], v29 offset:42688
	ds_read_b128 v[56:59], v29 offset:34240
	ds_read_b128 v[60:63], v28 offset:448
	v_cvt_f32_i32_e32 v28, v32
	s_waitcnt lgkmcnt(0)
	v_mfma_f32_16x16x32_bf16 v[48:51], v[56:59], v[60:63], v[48:51]
	v_mul_f32_e32 v29, v194, v28
	v_cmp_gt_f32_e32 vcc, s16, v29
	s_barrier
	v_mfma_f32_16x16x32_bf16 v[44:47], v[52:55], v[60:63], v[44:47]
	v_cndmask_b32_e32 v29, 0, v185, vcc
	v_fmac_f32_e32 v29, v194, v28
	v_exp_f32_e32 v28, v29
	v_cndmask_b32_e32 v29, 0, v193, vcc
	v_cmp_lt_i32_e32 vcc, v33, v32
	v_ldexp_f32 v28, v28, v29
	v_mul_f32_e32 v29, v28, v48
	v_mul_f32_e32 v40, v28, v49
	v_mul_f32_e32 v37, v28, v44
	v_mul_f32_e32 v43, v28, v45
	v_mul_f32_e32 v45, v28, v50
	v_mul_f32_e32 v46, v28, v46
	v_mul_f32_e32 v50, v28, v51
	v_mul_f32_e32 v47, v28, v47
	v_cvt_pk_bf16_f32 v28, v29, s0
	v_cvt_pk_bf16_f32 v29, v40, s0
	v_or_b32_e32 v44, 2, v33
	v_cndmask_b32_e64 v28, 0, v28, s[56:57]
	v_cndmask_b32_e32 v29, 0, v29, vcc
	v_or_b32_e32 v49, 3, v33
	v_perm_b32 v28, v29, v28, s19
	v_cvt_pk_bf16_f32 v29, v45, s0
	v_cmp_le_i32_e32 vcc, v44, v32
	v_cvt_pk_bf16_f32 v40, v50, s0
	v_or_b32_e32 v48, 18, v33
	v_cndmask_b32_e32 v29, 0, v29, vcc
	v_cmp_le_i32_e32 vcc, v49, v32
	v_or_b32_e32 v51, 19, v33
	v_cvt_pk_bf16_f32 v50, v144, v145
	v_cndmask_b32_e32 v40, 0, v40, vcc
	v_perm_b32 v29, v40, v29, s19
	v_mul_lo_u32 v40, v32, s20
	v_add_u32_e32 v40, s17, v40
	v_lshl_add_u32 v33, v33, 1, v40
	ds_write_b64 v33, v[28:29]
	v_cvt_pk_bf16_f32 v28, v37, s0
	v_cmp_le_i32_e32 vcc, v36, v32
	v_cvt_pk_bf16_f32 v29, v43, s0
	v_cvt_pk_bf16_f32 v33, v47, s0
	v_cndmask_b32_e32 v28, 0, v28, vcc
	v_cmp_le_i32_e32 vcc, v41, v32
	v_or_b32_e32 v43, s60, v199
	v_mul_lo_u32 v43, v43, s20
	v_cndmask_b32_e32 v29, 0, v29, vcc
	v_perm_b32 v28, v29, v28, s19
	v_cvt_pk_bf16_f32 v29, v46, s0
	v_cmp_le_i32_e32 vcc, v48, v32
	v_add_u32_e32 v43, s4, v43
	v_add_u32_e32 v196, v43, v200
	v_cndmask_b32_e32 v29, 0, v29, vcc
	v_cmp_le_i32_e32 vcc, v51, v32
	v_cvt_pk_bf16_f32 v51, v146, v147
	v_cvt_pk_bf16_f32 v52, v104, v105
	v_cndmask_b32_e32 v32, 0, v33, vcc
	v_perm_b32 v29, v32, v29, s19
	v_lshl_add_u32 v32, v36, 1, v40
	v_lshl_add_u64 v[40:41], s[68:69], 0, v[78:79]
	v_lshl_add_u64 v[26:27], v[40:41], 0, v[26:27]
	v_lshl_add_u64 v[30:31], v[40:41], 0, v[30:31]
	v_lshl_add_u64 v[34:35], v[40:41], 0, v[34:35]
	v_lshl_add_u64 v[38:39], v[40:41], 0, v[38:39]
	ds_write_b64 v32, v[28:29]
	s_waitcnt lgkmcnt(0)
	s_barrier
; #define LAS __attribute__((address_space(3)))
; #define RET_LOAD_K(ck, dst) do { \
;         _Pragma("unroll") for (int i = 0; i < 4; ++i) { const int id = tid + 512 * i, s_ = id >> 5, dc = id & 31; \
;             dst[i] = *(const u32x4*)(Kx + (size_t)seq_row(b, dir, (ck) * 64 + s_) * D + h * 256 + dc * 8); } } while (0)
; __device__ __forceinline__ void phase_ret_scan(KP P, const Ctx& c) {
;     ...
;             u32x4 pkn[4]; const bool has_next = ck + 1 < SLEN / 64;
;             if (has_next) RET_LOAD_K(ck + 1, pkn);
;             const LAS unsigned char* vtp = L + OFF_VT + (16 * w + r16) * TP + (8 * q4) * 2;
; #pragma unroll
;             for (int it = 0; it < 4; ++it) { const int i_ = 16 * it + r16; f32x4 a = (f32x4){0.f, 0.f, 0.f, 0.f};
;                 asm volatile("" ::: "memory");
; #pragma unroll
;                 for (int m = 0; m < 8; ++m) {
;                     const u32x4 t = (u32x4){cvt_pk_bf16(Racc[2 * m][0], Racc[2 * m][1]), cvt_pk_bf16(Racc[2 * m][2], Racc[2 * m][3]), cvt_pk_bf16(Racc[2 * m + 1][0], Racc[2 * m + 1][1]), cvt_pk_bf16(Racc[2 * m + 1][2], Racc[2 * m + 1][3])};
;                     const LAS unsigned char* qp = L + OFF_Q + i_ * QP + (32 * m + 4 * q4) * 2; const u32x2 lo = *(const LAS u32x2*)qp, hi = *(const LAS u32x2*)(qp + 32);
;                     const u32x4 tq = (u32x4){lo.x, lo.y, hi.x, hi.y}; a = __builtin_amdgcn_mfma_f32_16x16x32_bf16(__builtin_bit_cast(bf16x8, t), __builtin_bit_cast(bf16x8, tq), a, 0, 0, 0); }
;                 a = a * exp2f(lg2 * (float)(i_ + 1));
; #pragma unroll
;                 for (int ks = 0; ks < 2; ++ks) a = __builtin_amdgcn_mfma_f32_16x16x32_bf16(frag16(vtp + 64 * ks), frag16(L + OFF_P + i_ * TP + (32 * ks + 8 * q4) * 2), a, 0, 0, 0);
;                 *(u32x2*)(O + (size_t)seq_row(b, dir, ck * 64 + i_) * 4096 + h * 512 + dvs * 128 + 16 * w + 4 * q4) = (u32x2){cvt_pk_bf16(a[0], a[1]), cvt_pk_bf16(a[2], a[3])}; }
	global_load_dwordx4 v[26:29], v[26:27], off
	global_load_dwordx4 v[30:33], v[30:31], off
	global_load_dwordx4 v[34:37], v[34:35], off
	global_load_dwordx4 v[38:41], v[38:39], off
	v_mad_u32_u24 v238, v199, s15, v200
	v_mad_u32_u24 v78, v199, s20, v204
	ds_read_b128 v[214:217], v196
	ds_read_b128 v[218:221], v196 offset:64
	ds_read_b128 v[74:77], v238 offset:0
	ds_read_b128 v[206:209], v238 offset:64
	ds_read_b128 v[210:213], v238 offset:128
	ds_read_b128 v[222:225], v238 offset:192
	ds_read_b128 v[226:229], v238 offset:256
	ds_read_b128 v[230:233], v238 offset:320
	ds_read_b128 v[234:237], v238 offset:384
	ds_read_b128 v[240:243], v238 offset:448
	v_cvt_pk_bf16_f32 v50, v144, v145
	v_cvt_pk_bf16_f32 v51, v146, v147
	v_cvt_pk_bf16_f32 v52, v104, v105
	v_cvt_pk_bf16_f32 v53, v106, v107
	v_cvt_pk_bf16_f32 v58, v124, v125
	v_cvt_pk_bf16_f32 v59, v126, v127
	v_cvt_pk_bf16_f32 v60, v88, v89
	v_cvt_pk_bf16_f32 v61, v90, v91
	v_cvt_pk_bf16_f32 v70, v116, v117
	v_cvt_pk_bf16_f32 v71, v118, v119
	v_cvt_pk_bf16_f32 v72, v140, v141
	v_cvt_pk_bf16_f32 v73, v142, v143
	v_cvt_pk_bf16_f32 v42, v108, v109
	v_cvt_pk_bf16_f32 v43, v110, v111
	v_cvt_pk_bf16_f32 v44, v132, v133
	v_cvt_pk_bf16_f32 v45, v134, v135
	v_cvt_pk_bf16_f32 v46, v100, v101
	v_cvt_pk_bf16_f32 v47, v102, v103
	v_cvt_pk_bf16_f32 v48, v128, v129
	v_cvt_pk_bf16_f32 v49, v130, v131
	v_cvt_pk_bf16_f32 v54, v96, v97
	v_cvt_pk_bf16_f32 v55, v98, v99
	v_cvt_pk_bf16_f32 v56, v120, v121
	v_cvt_pk_bf16_f32 v57, v122, v123
	v_cvt_pk_bf16_f32 v66, v92, v93
	v_cvt_pk_bf16_f32 v67, v94, v95
	v_cvt_pk_bf16_f32 v68, v112, v113
	v_cvt_pk_bf16_f32 v69, v114, v115
	v_cvt_pk_bf16_f32 v62, v84, v85
	v_cvt_pk_bf16_f32 v63, v86, v87
	v_cvt_pk_bf16_f32 v64, v136, v137
	v_cvt_pk_bf16_f32 v65, v138, v139
	s_nop 1
	v_permlane32_swap_b32_e32 v50, v52
	v_permlane32_swap_b32_e32 v51, v53
	v_permlane32_swap_b32_e32 v58, v60
	v_permlane32_swap_b32_e32 v59, v61
	v_permlane32_swap_b32_e32 v70, v72
	v_permlane32_swap_b32_e32 v71, v73
	v_permlane32_swap_b32_e32 v42, v44
	v_permlane32_swap_b32_e32 v43, v45
	v_permlane32_swap_b32_e32 v46, v48
	v_permlane32_swap_b32_e32 v47, v49
	v_permlane32_swap_b32_e32 v54, v56
	v_permlane32_swap_b32_e32 v55, v57
	v_permlane32_swap_b32_e32 v66, v68
	v_permlane32_swap_b32_e32 v67, v69
	v_permlane32_swap_b32_e32 v62, v64
	v_permlane32_swap_b32_e32 v63, v65
	v_permlane16_swap_b32_e32 v50, v52
	v_permlane16_swap_b32_e32 v51, v53
	v_permlane16_swap_b32_e32 v58, v60
	v_permlane16_swap_b32_e32 v59, v61
	v_permlane16_swap_b32_e32 v70, v72
	v_permlane16_swap_b32_e32 v71, v73
	v_permlane16_swap_b32_e32 v42, v44
	v_permlane16_swap_b32_e32 v43, v45
	v_permlane16_swap_b32_e32 v46, v48
	v_permlane16_swap_b32_e32 v47, v49
	v_permlane16_swap_b32_e32 v54, v56
	v_permlane16_swap_b32_e32 v55, v57
	v_permlane16_swap_b32_e32 v66, v68
	v_permlane16_swap_b32_e32 v67, v69
	v_permlane16_swap_b32_e32 v62, v64
	v_permlane16_swap_b32_e32 v63, v65
	s_mov_b64 s[0:1], -1
	s_waitcnt lgkmcnt(7)
	v_mfma_f32_16x16x32_bf16 v[74:77], v[50:53], v[74:77], 0
	s_waitcnt lgkmcnt(6)
	v_mfma_f32_16x16x32_bf16 v[74:77], v[58:61], v[206:209], v[74:77]
	ds_read_b128 v[206:209], v78 offset:0
	s_waitcnt lgkmcnt(6)
	v_mfma_f32_16x16x32_bf16 v[74:77], v[70:73], v[210:213], v[74:77]
	ds_read_b128 v[210:213], v78 offset:64
	s_waitcnt lgkmcnt(6)
	v_mfma_f32_16x16x32_bf16 v[74:77], v[42:45], v[222:225], v[74:77]
	s_waitcnt lgkmcnt(5)
	v_mfma_f32_16x16x32_bf16 v[74:77], v[46:49], v[226:229], v[74:77]
	s_waitcnt lgkmcnt(4)
	v_mfma_f32_16x16x32_bf16 v[74:77], v[54:57], v[230:233], v[74:77]
	v_add_u32_e32 v245, 1, v199
	v_cvt_f32_ubyte0_e32 v245, v245
	v_mul_f32_e32 v246, v194, v245
	v_cmp_gt_f32_e32 vcc, s16, v246
	s_waitcnt lgkmcnt(3)
	v_mfma_f32_16x16x32_bf16 v[74:77], v[66:69], v[234:237], v[74:77]
	s_waitcnt lgkmcnt(2)
	v_mfma_f32_16x16x32_bf16 v[74:77], v[62:65], v[240:243], v[74:77]
	v_cndmask_b32_e32 v246, 0, v185, vcc
	v_fmac_f32_e32 v246, v194, v245
	v_exp_f32_e32 v245, v246
	v_cndmask_b32_e32 v246, 0, v193, vcc
	s_and_b64 vcc, exec, s[38:39]
	v_ldexp_f32 v246, v245, v246
	s_nop 1
	v_pk_mul_f32 v[76:77], v[246:247], v[76:77] op_sel_hi:[0,1]
	v_pk_mul_f32 v[74:75], v[246:247], v[74:75] op_sel_hi:[0,1]
	s_waitcnt lgkmcnt(1)
	s_nop 0
	v_mfma_f32_16x16x32_bf16 v[74:77], v[214:217], v[206:209], v[74:77]
	s_waitcnt lgkmcnt(0)
	v_mfma_f32_16x16x32_bf16 v[74:77], v[218:221], v[210:213], v[74:77]
	s_cbranch_vccz .LBB0_2556
	v_add_u32_e32 v78, 0xffffff00, v202
	v_cndmask_b32_e64 v78, v203, v78, s[54:55]
	v_add_u32_e32 v158, s22, v78
	s_mov_b64 s[0:1], 0

; #define LAS __attribute__((address_space(3)))
; __device__ __forceinline__ void phase_ret_scan(KP P, const Ctx& c) {
;     ...
; #pragma unroll
;             for (int it = 0; it < 4; ++it) { const int i_ = 16 * it + r16; f32x4 a = (f32x4){0.f, 0.f, 0.f, 0.f};
;                 asm volatile("" ::: "memory");
; #pragma unroll
;                 for (int m = 0; m < 8; ++m) {
;                     const u32x4 t = (u32x4){cvt_pk_bf16(Racc[2 * m][0], Racc[2 * m][1]), cvt_pk_bf16(Racc[2 * m][2], Racc[2 * m][3]), cvt_pk_bf16(Racc[2 * m + 1][0], Racc[2 * m + 1][1]), cvt_pk_bf16(Racc[2 * m + 1][2], Racc[2 * m + 1][3])};
;                     const LAS unsigned char* qp = L + OFF_Q + i_ * QP + (32 * m + 4 * q4) * 2; const u32x2 lo = *(const LAS u32x2*)qp, hi = *(const LAS u32x2*)(qp + 32);
;                     const u32x4 tq = (u32x4){lo.x, lo.y, hi.x, hi.y}; a = __builtin_amdgcn_mfma_f32_16x16x32_bf16(__builtin_bit_cast(bf16x8, t), __builtin_bit_cast(bf16x8, tq), a, 0, 0, 0); }
;                 a = a * exp2f(lg2 * (float)(i_ + 1));
; #pragma unroll
;                 for (int ks = 0; ks < 2; ++ks) a = __builtin_amdgcn_mfma_f32_16x16x32_bf16(frag16(vtp + 64 * ks), frag16(L + OFF_P + i_ * TP + (32 * ks + 8 * q4) * 2), a, 0, 0, 0);
;                 *(u32x2*)(O + (size_t)seq_row(b, dir, ck * 64 + i_) * 4096 + h * 512 + dvs * 128 + 16 * w + 4 * q4) = (u32x2){cvt_pk_bf16(a[0], a[1]), cvt_pk_bf16(a[2], a[3])}; }
.LBB0_2558:
	v_lshlrev_b32_e32 v78, 1, v156
	v_ashrrev_i32_e32 v159, 31, v158
	v_lshl_add_u64 v[156:157], s[62:63], 0, v[78:79]
	s_nop 1
	v_cvt_pk_bf16_f32 v74, v74, v75
	v_cvt_pk_bf16_f32 v75, v76, v77
	v_lshlrev_b64 v[76:77], 13, v[158:159]
	v_mul_u32_u24_e32 v206, 0x210, v199
	v_lshl_add_u64 v[76:77], v[156:157], 0, v[76:77]
	global_store_dwordx2 v[76:77], v[74:75], off
	v_add_u32_e32 v78, v206, v205
	v_add_u32_e32 v158, 0x2000, v78
	ds_read_b128 v[74:77], v238 offset:8448
	ds_read_b128 v[206:209], v238 offset:8512
	ds_read_b128 v[210:213], v238 offset:8576
	ds_read_b128 v[222:225], v238 offset:8640
	ds_read_b128 v[226:229], v238 offset:8704
	ds_read_b128 v[230:233], v238 offset:8768
	ds_read_b128 v[234:237], v238 offset:8832
	ds_read_b128 v[240:243], v238 offset:8896
	v_mul_u32_u24_e32 v201, 0x90, v199
	v_add_u32_e32 v204, v201, v204
	s_mov_b64 s[0:1], -1
	s_waitcnt lgkmcnt(7)
	v_mfma_f32_16x16x32_bf16 v[74:77], v[50:53], v[74:77], 0
	s_waitcnt lgkmcnt(6)
	v_mfma_f32_16x16x32_bf16 v[74:77], v[58:61], v[206:209], v[74:77]
	ds_read_b128 v[206:209], v204 offset:2304
	s_waitcnt lgkmcnt(6)
	v_mfma_f32_16x16x32_bf16 v[74:77], v[70:73], v[210:213], v[74:77]
	ds_read_b128 v[210:213], v204 offset:2368
	s_waitcnt lgkmcnt(6)
	v_mfma_f32_16x16x32_bf16 v[74:77], v[42:45], v[222:225], v[74:77]
	s_waitcnt lgkmcnt(5)
	v_mfma_f32_16x16x32_bf16 v[74:77], v[46:49], v[226:229], v[74:77]
	s_waitcnt lgkmcnt(4)
	v_mfma_f32_16x16x32_bf16 v[74:77], v[54:57], v[230:233], v[74:77]
	v_add_u32_e32 v245, 17, v199
	v_cvt_f32_ubyte0_e32 v245, v245
	v_mul_f32_e32 v246, v194, v245
	v_cmp_gt_f32_e32 vcc, s16, v246
	s_waitcnt lgkmcnt(3)
	v_mfma_f32_16x16x32_bf16 v[74:77], v[66:69], v[234:237], v[74:77]
	s_waitcnt lgkmcnt(2)
	v_mfma_f32_16x16x32_bf16 v[74:77], v[62:65], v[240:243], v[74:77]
	v_cndmask_b32_e32 v246, 0, v185, vcc
	v_fmac_f32_e32 v246, v194, v245
	v_exp_f32_e32 v245, v246
	v_cndmask_b32_e32 v246, 0, v193, vcc
	s_andn2_b64 vcc, exec, s[38:39]
	v_ldexp_f32 v246, v245, v246
	s_nop 1
	v_pk_mul_f32 v[76:77], v[246:247], v[76:77] op_sel_hi:[0,1]
	v_pk_mul_f32 v[74:75], v[246:247], v[74:75] op_sel_hi:[0,1]
	v_cndmask_b32_e64 v158, 0, 1, s[38:39]
	v_cmp_ne_u32_e64 s[56:57], 1, v158
	s_waitcnt lgkmcnt(1)
	s_nop 0
	v_mfma_f32_16x16x32_bf16 v[74:77], v[214:217], v[206:209], v[74:77]
	s_waitcnt lgkmcnt(0)
	v_mfma_f32_16x16x32_bf16 v[74:77], v[218:221], v[210:213], v[74:77]
	s_cbranch_vccnz .LBB0_2560
	v_add_u32_e32 v158, 0xffffff10, v202
	v_add_u32_e32 v159, -16, v203
	v_cndmask_b32_e64 v158, v159, v158, s[54:55]
	v_add_u32_e32 v158, s22, v158
	s_mov_b64 s[0:1], 0

; #define LAS __attribute__((address_space(3)))
; __device__ __forceinline__ void phase_ret_scan(KP P, const Ctx& c) {
;     ...
; #pragma unroll
;             for (int it = 0; it < 4; ++it) { const int i_ = 16 * it + r16; f32x4 a = (f32x4){0.f, 0.f, 0.f, 0.f};
;                 asm volatile("" ::: "memory");
; #pragma unroll
;                 for (int m = 0; m < 8; ++m) {
;                     const u32x4 t = (u32x4){cvt_pk_bf16(Racc[2 * m][0], Racc[2 * m][1]), cvt_pk_bf16(Racc[2 * m][2], Racc[2 * m][3]), cvt_pk_bf16(Racc[2 * m + 1][0], Racc[2 * m + 1][1]), cvt_pk_bf16(Racc[2 * m + 1][2], Racc[2 * m + 1][3])};
;                     const LAS unsigned char* qp = L + OFF_Q + i_ * QP + (32 * m + 4 * q4) * 2; const u32x2 lo = *(const LAS u32x2*)qp, hi = *(const LAS u32x2*)(qp + 32);
;                     const u32x4 tq = (u32x4){lo.x, lo.y, hi.x, hi.y}; a = __builtin_amdgcn_mfma_f32_16x16x32_bf16(__builtin_bit_cast(bf16x8, t), __builtin_bit_cast(bf16x8, tq), a, 0, 0, 0); }
;                 a = a * exp2f(lg2 * (float)(i_ + 1));
; #pragma unroll
;                 for (int ks = 0; ks < 2; ++ks) a = __builtin_amdgcn_mfma_f32_16x16x32_bf16(frag16(vtp + 64 * ks), frag16(L + OFF_P + i_ * TP + (32 * ks + 8 * q4) * 2), a, 0, 0, 0);
;                 *(u32x2*)(O + (size_t)seq_row(b, dir, ck * 64 + i_) * 4096 + h * 512 + dvs * 128 + 16 * w + 4 * q4) = (u32x2){cvt_pk_bf16(a[0], a[1]), cvt_pk_bf16(a[2], a[3])}; }
.LBB0_2562:
	v_ashrrev_i32_e32 v159, 31, v158
	s_nop 3
	v_cvt_pk_bf16_f32 v74, v74, v75
	v_cvt_pk_bf16_f32 v75, v76, v77
	v_lshlrev_b64 v[76:77], 13, v[158:159]
	v_lshl_add_u64 v[76:77], v[156:157], 0, v[76:77]
	global_store_dwordx2 v[76:77], v[74:75], off
	v_add_u32_e32 v158, 0x4000, v78
	ds_read_b128 v[74:77], v238 offset:16896
	ds_read_b128 v[206:209], v238 offset:16960
	ds_read_b128 v[210:213], v238 offset:17024
	ds_read_b128 v[222:225], v238 offset:17088
	ds_read_b128 v[226:229], v238 offset:17152
	ds_read_b128 v[230:233], v238 offset:17216
	ds_read_b128 v[234:237], v238 offset:17280
	ds_read_b128 v[240:243], v238 offset:17344
	s_mov_b64 s[0:1], -1
	s_waitcnt lgkmcnt(7)
	v_mfma_f32_16x16x32_bf16 v[74:77], v[50:53], v[74:77], 0
	s_waitcnt lgkmcnt(6)
	v_mfma_f32_16x16x32_bf16 v[74:77], v[58:61], v[206:209], v[74:77]
	ds_read_b128 v[206:209], v204 offset:4608
	s_waitcnt lgkmcnt(6)
	v_mfma_f32_16x16x32_bf16 v[74:77], v[70:73], v[210:213], v[74:77]
	ds_read_b128 v[210:213], v204 offset:4672
	s_waitcnt lgkmcnt(6)
	v_mfma_f32_16x16x32_bf16 v[74:77], v[42:45], v[222:225], v[74:77]
	s_waitcnt lgkmcnt(5)
	v_mfma_f32_16x16x32_bf16 v[74:77], v[46:49], v[226:229], v[74:77]
	s_waitcnt lgkmcnt(4)
	v_mfma_f32_16x16x32_bf16 v[74:77], v[54:57], v[230:233], v[74:77]
	v_add_u32_e32 v245, 33, v199
	v_cvt_f32_ubyte0_e32 v245, v245
	v_mul_f32_e32 v246, v194, v245
	v_cmp_gt_f32_e32 vcc, s16, v246
	s_waitcnt lgkmcnt(3)
	v_mfma_f32_16x16x32_bf16 v[74:77], v[66:69], v[234:237], v[74:77]
	s_waitcnt lgkmcnt(2)
	v_mfma_f32_16x16x32_bf16 v[74:77], v[62:65], v[240:243], v[74:77]
	v_cndmask_b32_e32 v246, 0, v185, vcc
	v_fmac_f32_e32 v246, v194, v245
	v_exp_f32_e32 v245, v246
	v_cndmask_b32_e32 v246, 0, v193, vcc
	s_and_b64 vcc, exec, s[56:57]
	v_ldexp_f32 v246, v245, v246
	s_nop 1
	v_pk_mul_f32 v[76:77], v[246:247], v[76:77] op_sel_hi:[0,1]
	v_pk_mul_f32 v[74:75], v[246:247], v[74:75] op_sel_hi:[0,1]
	s_waitcnt lgkmcnt(1)
	s_nop 0
	v_mfma_f32_16x16x32_bf16 v[74:77], v[214:217], v[206:209], v[74:77]
	s_waitcnt lgkmcnt(0)
	v_mfma_f32_16x16x32_bf16 v[74:77], v[218:221], v[210:213], v[74:77]
	s_cbranch_vccnz .LBB0_2564
	v_add_u32_e32 v158, 0xffffff20, v202
	v_subrev_u32_e32 v159, 32, v203
	v_cndmask_b32_e64 v158, v159, v158, s[54:55]
	v_add_u32_e32 v158, s22, v158
	s_mov_b64 s[0:1], 0

; #define LAS __attribute__((address_space(3)))
; __device__ __forceinline__ void phase_ret_scan(KP P, const Ctx& c) {
;     ...
; #pragma unroll
;             for (int it = 0; it < 4; ++it) { const int i_ = 16 * it + r16; f32x4 a = (f32x4){0.f, 0.f, 0.f, 0.f};
;                 asm volatile("" ::: "memory");
; #pragma unroll
;                 for (int m = 0; m < 8; ++m) {
;                     const u32x4 t = (u32x4){cvt_pk_bf16(Racc[2 * m][0], Racc[2 * m][1]), cvt_pk_bf16(Racc[2 * m][2], Racc[2 * m][3]), cvt_pk_bf16(Racc[2 * m + 1][0], Racc[2 * m + 1][1]), cvt_pk_bf16(Racc[2 * m + 1][2], Racc[2 * m + 1][3])};
;                     const LAS unsigned char* qp = L + OFF_Q + i_ * QP + (32 * m + 4 * q4) * 2; const u32x2 lo = *(const LAS u32x2*)qp, hi = *(const LAS u32x2*)(qp + 32);
;                     const u32x4 tq = (u32x4){lo.x, lo.y, hi.x, hi.y}; a = __builtin_amdgcn_mfma_f32_16x16x32_bf16(__builtin_bit_cast(bf16x8, t), __builtin_bit_cast(bf16x8, tq), a, 0, 0, 0); }
;                 a = a * exp2f(lg2 * (float)(i_ + 1));
; #pragma unroll
;                 for (int ks = 0; ks < 2; ++ks) a = __builtin_amdgcn_mfma_f32_16x16x32_bf16(frag16(vtp + 64 * ks), frag16(L + OFF_P + i_ * TP + (32 * ks + 8 * q4) * 2), a, 0, 0, 0);
;                 *(u32x2*)(O + (size_t)seq_row(b, dir, ck * 64 + i_) * 4096 + h * 512 + dvs * 128 + 16 * w + 4 * q4) = (u32x2){cvt_pk_bf16(a[0], a[1]), cvt_pk_bf16(a[2], a[3])}; }
.LBB0_2566:
	v_ashrrev_i32_e32 v159, 31, v158
	s_nop 3
	v_cvt_pk_bf16_f32 v74, v74, v75
	v_cvt_pk_bf16_f32 v75, v76, v77
	v_lshlrev_b64 v[76:77], 13, v[158:159]
	v_lshl_add_u64 v[76:77], v[156:157], 0, v[76:77]
	global_store_dwordx2 v[76:77], v[74:75], off
	v_add_u32_e32 v78, 0x6000, v78
	ds_read_b128 v[74:77], v238 offset:25344
	ds_read_b128 v[206:209], v238 offset:25408
	ds_read_b128 v[210:213], v238 offset:25472
	ds_read_b128 v[222:225], v238 offset:25536
	ds_read_b128 v[226:229], v238 offset:25600
	ds_read_b128 v[230:233], v238 offset:25664
	ds_read_b128 v[234:237], v238 offset:25728
	ds_read_b128 v[240:243], v238 offset:25792
	s_mov_b64 s[0:1], -1
	s_waitcnt lgkmcnt(7)
	v_mfma_f32_16x16x32_bf16 v[50:53], v[50:53], v[74:77], 0
	s_waitcnt lgkmcnt(6)
	v_mfma_f32_16x16x32_bf16 v[50:53], v[58:61], v[206:209], v[50:53]
	ds_read_b128 v[206:209], v204 offset:6912
	s_waitcnt lgkmcnt(6)
	v_mfma_f32_16x16x32_bf16 v[50:53], v[70:73], v[210:213], v[50:53]
	ds_read_b128 v[210:213], v204 offset:6976
	s_waitcnt lgkmcnt(6)
	v_mfma_f32_16x16x32_bf16 v[42:45], v[42:45], v[222:225], v[50:53]
	s_waitcnt lgkmcnt(5)
	v_mfma_f32_16x16x32_bf16 v[42:45], v[46:49], v[226:229], v[42:45]
	s_waitcnt lgkmcnt(4)
	v_mfma_f32_16x16x32_bf16 v[42:45], v[54:57], v[230:233], v[42:45]
	v_add_u32_e32 v245, 49, v199
	v_cvt_f32_ubyte0_e32 v245, v245
	v_mul_f32_e32 v246, v194, v245
	v_cmp_gt_f32_e32 vcc, s16, v246
	s_waitcnt lgkmcnt(3)
	v_mfma_f32_16x16x32_bf16 v[42:45], v[66:69], v[234:237], v[42:45]
	s_waitcnt lgkmcnt(2)
	v_mfma_f32_16x16x32_bf16 v[42:45], v[62:65], v[240:243], v[42:45]
	v_cndmask_b32_e32 v246, 0, v185, vcc
	v_fmac_f32_e32 v246, v194, v245
	v_exp_f32_e32 v245, v246
	v_cndmask_b32_e32 v246, 0, v193, vcc
	s_and_b64 vcc, exec, s[56:57]
	v_ldexp_f32 v246, v245, v246
	s_nop 1
	v_pk_mul_f32 v[44:45], v[246:247], v[44:45] op_sel_hi:[0,1]
	v_pk_mul_f32 v[42:43], v[246:247], v[42:43] op_sel_hi:[0,1]
	s_waitcnt lgkmcnt(1)
	s_nop 0
	v_mfma_f32_16x16x32_bf16 v[42:45], v[214:217], v[206:209], v[42:45]
	s_waitcnt lgkmcnt(0)
	v_mfma_f32_16x16x32_bf16 v[42:45], v[218:221], v[210:213], v[42:45]
	s_cbranch_vccnz .LBB0_2568
	v_add_u32_e32 v46, 0xffffff30, v202
	v_subrev_u32_e32 v47, 48, v203
	v_cndmask_b32_e64 v46, v47, v46, s[54:55]
	v_add_u32_e32 v46, s22, v46
	s_mov_b64 s[0:1], 0
